# grid barrier: the XCD leader's acquire invalidate is issued right behind its top-counter arrival atomic, and spinning workgroups invalidate before they spin
# speedup vs baseline: 1.0063x; 1.0063x over previous
; __device__ __forceinline__ unsigned xb_ld(unsigned* p)              { return __hip_atomic_load(p, __ATOMIC_RELAXED, __HIP_MEMORY_SCOPE_AGENT); }
; __device__ __forceinline__ unsigned xb_add(unsigned* p, unsigned v) { return __hip_atomic_fetch_add(p, v, __ATOMIC_RELAXED, __HIP_MEMORY_SCOPE_AGENT); }
; #define XB_SPIN(cond, bar) do { unsigned _sp = 0; while (cond) { __builtin_amdgcn_s_sleep(1); \
;     if ((++_sp & 255u) == 0u) { if (xb_ld(&(bar)[XB_TMO])) break; if (_sp > XB_SPIN_CAP) { atomicAdd(&(bar)[XB_TMO], 1u); break; } } } } while (0)
; __device__ __forceinline__ void xcd_barrier(unsigned* bar, volatile LAS unsigned* st, int wv0) {
;     ...
;         const unsigned old = xb_add(&bar[XB_XSUB(x)], 1u);
;         const unsigned gen = old / nloc;
;         if (old + 1u == (gen + 1u) * nloc) {
;             __builtin_amdgcn_fence(__ATOMIC_RELEASE, "agent");
;             asm volatile("s_waitcnt vmcnt(0)" ::: "memory");
;             const unsigned og = xb_add(&bar[XB_TOP], 1u);
;             const unsigned tg = og / nx;
;             if (og + 1u == (tg + 1u) * nx) xb_add(&bar[XB_TOPGEN], 1u);
;             else XB_SPIN(xb_ld(&bar[XB_TOPGEN]) == tg, bar);
;             __builtin_amdgcn_fence(__ATOMIC_ACQUIRE, "agent");
.LBB0_550:
	s_andn2_saveexec_b64 s[6:7], s[6:7]
	s_cbranch_execz .LBB0_570
	s_mov_b64 s[8:9], exec
	buffer_wbl2 sc1
	s_waitcnt lgkmcnt(0)
	s_waitcnt vmcnt(0)
	v_mbcnt_lo_u32_b32 v1, s8, 0
	v_mbcnt_hi_u32_b32 v1, s9, v1
	v_cmp_eq_u32_e32 vcc, 0, v1
	s_and_saveexec_b64 s[12:13], vcc
	s_cbranch_execz .LBB0_553
	s_bcnt1_i32_b64 s0, s[8:9]
	v_mov_b32_e32 v2, s0
	global_atomic_add v2, v250, v2, s[10:11] offset:1024 sc0
	buffer_inv sc1

; __device__ __forceinline__ unsigned xb_add(unsigned* p, unsigned v) { return __hip_atomic_fetch_add(p, v, __ATOMIC_RELAXED, __HIP_MEMORY_SCOPE_AGENT); }
; __device__ __forceinline__ void xcd_barrier(unsigned* bar, volatile LAS unsigned* st, int wv0) {
;     ...
;             __builtin_amdgcn_fence(__ATOMIC_ACQUIRE, "agent");
;             xb_add(&bar[XB_XGEN(x)], 1u);
;             asm volatile("s_waitcnt vmcnt(0)" ::: "memory");
.LBB0_567:
	s_or_b64 exec, exec, s[8:9]
	s_mov_b64 s[8:9], exec
	v_mbcnt_lo_u32_b32 v0, s8, 0
	v_mbcnt_hi_u32_b32 v0, s9, v0
	v_cmp_eq_u32_e32 vcc, 0, v0
	s_waitcnt vmcnt(0)
	s_and_saveexec_b64 s[10:11], vcc
	s_cbranch_execz .LBB0_569
	s_bcnt1_i32_b64 s0, s[8:9]
	v_mov_b32_e32 v0, s0
	global_atomic_add v231, v0, s[4:5] offset:1024

; __device__ __forceinline__ unsigned xb_ld(unsigned* p)              { return __hip_atomic_load(p, __ATOMIC_RELAXED, __HIP_MEMORY_SCOPE_AGENT); }
; __device__ __forceinline__ unsigned xb_add(unsigned* p, unsigned v) { return __hip_atomic_fetch_add(p, v, __ATOMIC_RELAXED, __HIP_MEMORY_SCOPE_AGENT); }
; #define XB_SPIN(cond, bar) do { unsigned _sp = 0; while (cond) { __builtin_amdgcn_s_sleep(1); \
;     if ((++_sp & 255u) == 0u) { if (xb_ld(&(bar)[XB_TMO])) break; if (_sp > XB_SPIN_CAP) { atomicAdd(&(bar)[XB_TMO], 1u); break; } } } } while (0)
; __device__ __forceinline__ void xcd_barrier(unsigned* bar, volatile LAS unsigned* st, int wv0) {
;     ...
;         if (old + 1u == (gen + 1u) * nloc) {
;             __builtin_amdgcn_fence(__ATOMIC_RELEASE, "agent");
;             asm volatile("s_waitcnt vmcnt(0)" ::: "memory");
;             const unsigned og = xb_add(&bar[XB_TOP], 1u);
;             const unsigned tg = og / nx;
;             if (og + 1u == (tg + 1u) * nx) xb_add(&bar[XB_TOPGEN], 1u);
;             else XB_SPIN(xb_ld(&bar[XB_TOPGEN]) == tg, bar);
.LBB0_642:
	s_andn2_saveexec_b64 s[2:3], s[2:3]
	s_cbranch_execz .LBB0_658
	v_add_co_u32_e32 v6, vcc, 0x27743000, v0
	buffer_wbl2 sc1
	s_waitcnt lgkmcnt(0)
	s_waitcnt vmcnt(0)
	v_addc_co_u32_e32 v7, vcc, 0, v1, vcc
	v_mov_b32_e32 v5, 1
	global_atomic_add v5, v[6:7], v5, off offset:1024 sc0
	buffer_inv sc1
	v_cvt_f32_u32_e32 v6, v4
	v_sub_u32_e32 v7, 0, v4
	s_mov_b64 s[6:7], -1
	v_rcp_iflag_f32_e32 v6, v6
	s_nop 0
	v_mul_f32_e32 v6, 0x4f7ffffe, v6
	v_cvt_u32_f32_e32 v6, v6
	v_mul_lo_u32 v7, v7, v6
	v_mul_hi_u32 v7, v6, v7
	v_add_u32_e32 v6, v6, v7
	s_waitcnt vmcnt(0)
	v_mul_hi_u32 v6, v5, v6
	v_mul_lo_u32 v7, v6, v4
	v_sub_u32_e32 v7, v5, v7
	v_cmp_ge_u32_e32 vcc, v7, v4
	v_add_u32_e32 v8, 1, v6
	s_nop 0
	v_cndmask_b32_e32 v6, v6, v8, vcc
	v_sub_u32_e32 v8, v7, v4
	v_cndmask_b32_e32 v7, v7, v8, vcc
	v_cmp_ge_u32_e32 vcc, v7, v4
	v_add_u32_e32 v7, 1, v6
	s_nop 0
	v_cndmask_b32_e32 v8, v6, v7, vcc
	v_add_u32_e32 v6, 1, v5
	v_mad_u64_u32 v[4:5], s[0:1], v4, v8, v[4:5]
	s_mov_b64 s[0:1], 0x27743500
	v_cmp_ne_u32_e32 vcc, v6, v4
	v_lshl_add_u64 v[4:5], v[0:1], 0, s[0:1]
	s_and_saveexec_b64 s[4:5], vcc
	s_cbranch_execz .LBB0_655
	global_load_dword v6, v[4:5], off sc1
	s_mov_b64 s[8:9], 0
	s_waitcnt vmcnt(0)
	v_cmp_eq_u32_e32 vcc, v6, v8
	s_and_saveexec_b64 s[6:7], vcc
	s_cbranch_execz .LBB0_654
	s_mov_b64 s[0:1], 0x27740200
	v_lshl_add_u64 v[6:7], v[0:1], 0, s[0:1]
	s_mov_b32 s0, 1
	s_branch .LBB0_647

; __device__ __forceinline__ unsigned xb_add(unsigned* p, unsigned v) { return __hip_atomic_fetch_add(p, v, __ATOMIC_RELAXED, __HIP_MEMORY_SCOPE_AGENT); }
; __device__ __forceinline__ void xcd_barrier(unsigned* bar, volatile LAS unsigned* st, int wv0) {
;     ...
;             __builtin_amdgcn_fence(__ATOMIC_ACQUIRE, "agent");
;             xb_add(&bar[XB_XGEN(x)], 1u);
;             asm volatile("s_waitcnt vmcnt(0)" ::: "memory");
.LBB0_657:
	s_or_b64 exec, exec, s[4:5]
	v_add_co_u32_e32 v0, vcc, 0x2000, v2
	v_mov_b32_e32 v2, 1
	s_nop 0
	v_addc_co_u32_e32 v1, vcc, 0, v3, vcc
	s_waitcnt vmcnt(0)
	global_atomic_add v[0:1], v2, off offset:1024
	s_waitcnt vmcnt(0)

; __device__ __forceinline__ unsigned xb_add(unsigned* p, unsigned v) { return __hip_atomic_fetch_add(p, v, __ATOMIC_RELAXED, __HIP_MEMORY_SCOPE_AGENT); }
; __device__ __forceinline__ void xcd_barrier(unsigned* bar, volatile LAS unsigned* st, int wv0) {
;     ...
;         const unsigned old = xb_add(&bar[XB_XSUB(x)], 1u);
;         const unsigned gen = old / nloc;
;         if (old + 1u == (gen + 1u) * nloc) {
;             __builtin_amdgcn_fence(__ATOMIC_RELEASE, "agent");
;             asm volatile("s_waitcnt vmcnt(0)" ::: "memory");
;             const unsigned og = xb_add(&bar[XB_TOP], 1u);
.LBB0_799:
	s_andn2_saveexec_b64 s[6:7], s[6:7]
	s_cbranch_execz .LBB0_819
	s_mov_b64 s[8:9], exec
	buffer_wbl2 sc1
	s_waitcnt lgkmcnt(0)
	s_waitcnt vmcnt(0)
	v_mbcnt_lo_u32_b32 v1, s8, 0
	v_mbcnt_hi_u32_b32 v1, s9, v1
	v_cmp_eq_u32_e32 vcc, 0, v1
	s_and_saveexec_b64 s[10:11], vcc
	s_cbranch_execz .LBB0_802
	s_bcnt1_i32_b64 s0, s[8:9]
	v_mov_b32_e32 v2, s0
	global_atomic_add v2, v250, v2, s[86:87] offset:1024 sc0
	buffer_inv sc1

; __device__ __forceinline__ unsigned xb_add(unsigned* p, unsigned v) { return __hip_atomic_fetch_add(p, v, __ATOMIC_RELAXED, __HIP_MEMORY_SCOPE_AGENT); }
; __device__ __forceinline__ void xcd_barrier(unsigned* bar, volatile LAS unsigned* st, int wv0) {
;     ...
;         const unsigned old = xb_add(&bar[XB_XSUB(x)], 1u);
;         const unsigned gen = old / nloc;
;         if (old + 1u == (gen + 1u) * nloc) {
;             __builtin_amdgcn_fence(__ATOMIC_RELEASE, "agent");
;             asm volatile("s_waitcnt vmcnt(0)" ::: "memory");
;             const unsigned og = xb_add(&bar[XB_TOP], 1u);
.LBB0_878:
	s_andn2_saveexec_b64 s[8:9], s[8:9]
	s_cbranch_execz .LBB0_898
	s_mov_b64 s[10:11], exec
	buffer_wbl2 sc1
	s_waitcnt lgkmcnt(0)
	s_waitcnt vmcnt(0)
	v_mbcnt_lo_u32_b32 v1, s10, 0
	v_mbcnt_hi_u32_b32 v1, s11, v1
	v_cmp_eq_u32_e32 vcc, 0, v1
	s_and_saveexec_b64 s[12:13], vcc
	s_cbranch_execz .LBB0_881
	s_bcnt1_i32_b64 s0, s[10:11]
	v_mov_b32_e32 v2, s0
	global_atomic_add v2, v250, v2, s[4:5] offset:1024 sc0
	buffer_inv sc1

; __device__ __forceinline__ unsigned xb_add(unsigned* p, unsigned v) { return __hip_atomic_fetch_add(p, v, __ATOMIC_RELAXED, __HIP_MEMORY_SCOPE_AGENT); }
; __device__ __forceinline__ void xcd_barrier(unsigned* bar, volatile LAS unsigned* st, int wv0) {
;     ...
;             __builtin_amdgcn_fence(__ATOMIC_ACQUIRE, "agent");
;             xb_add(&bar[XB_XGEN(x)], 1u);
;             asm volatile("s_waitcnt vmcnt(0)" ::: "memory");
.LBB0_895:
	s_or_b64 exec, exec, s[4:5]
	s_mov_b64 s[4:5], exec
	v_mbcnt_lo_u32_b32 v0, s4, 0
	v_mbcnt_hi_u32_b32 v0, s5, v0
	v_cmp_eq_u32_e32 vcc, 0, v0
	s_waitcnt vmcnt(0)
	s_and_saveexec_b64 s[10:11], vcc
	s_cbranch_execz .LBB0_897
	s_bcnt1_i32_b64 s0, s[4:5]
	v_mov_b32_e32 v0, s0
	global_atomic_add v231, v0, s[6:7] offset:1024

; __device__ __forceinline__ unsigned xb_add(unsigned* p, unsigned v) { return __hip_atomic_fetch_add(p, v, __ATOMIC_RELAXED, __HIP_MEMORY_SCOPE_AGENT); }
; __device__ __forceinline__ void xcd_barrier(unsigned* bar, volatile LAS unsigned* st, int wv0) {
;     ...
;         const unsigned old = xb_add(&bar[XB_XSUB(x)], 1u);
;         const unsigned gen = old / nloc;
;         if (old + 1u == (gen + 1u) * nloc) {
;             __builtin_amdgcn_fence(__ATOMIC_RELEASE, "agent");
;             asm volatile("s_waitcnt vmcnt(0)" ::: "memory");
;             const unsigned og = xb_add(&bar[XB_TOP], 1u);
.LBB0_1466:
	s_andn2_saveexec_b64 s[6:7], s[6:7]
	s_cbranch_execz .LBB0_1486
	s_mov_b64 s[10:11], exec
	buffer_wbl2 sc1
	s_waitcnt lgkmcnt(0)
	s_waitcnt vmcnt(0)
	v_mbcnt_lo_u32_b32 v1, s10, 0
	v_mbcnt_hi_u32_b32 v1, s11, v1
	v_cmp_eq_u32_e32 vcc, 0, v1
	s_and_saveexec_b64 s[12:13], vcc
	s_cbranch_execz .LBB0_1469
	s_bcnt1_i32_b64 s0, s[10:11]
	v_mov_b32_e32 v2, s0
	global_atomic_add v2, v250, v2, s[8:9] offset:1024 sc0
	buffer_inv sc1

; __device__ __forceinline__ unsigned xb_add(unsigned* p, unsigned v) { return __hip_atomic_fetch_add(p, v, __ATOMIC_RELAXED, __HIP_MEMORY_SCOPE_AGENT); }
; __device__ __forceinline__ void xcd_barrier(unsigned* bar, volatile LAS unsigned* st, int wv0) {
;     ...
;         const unsigned old = xb_add(&bar[XB_XSUB(x)], 1u);
;         const unsigned gen = old / nloc;
;         if (old + 1u == (gen + 1u) * nloc) {
;             __builtin_amdgcn_fence(__ATOMIC_RELEASE, "agent");
;             asm volatile("s_waitcnt vmcnt(0)" ::: "memory");
;             const unsigned og = xb_add(&bar[XB_TOP], 1u);
.LBB0_1643:
	s_mov_b64 s[10:11], exec
	buffer_wbl2 sc1
	s_waitcnt lgkmcnt(0)
	s_waitcnt vmcnt(0)
	v_mbcnt_lo_u32_b32 v1, s10, 0
	v_mbcnt_hi_u32_b32 v1, s11, v1
	v_cmp_eq_u32_e32 vcc, 0, v1
	s_and_saveexec_b64 s[12:13], vcc
	s_cbranch_execz .LBB0_1645
	s_bcnt1_i32_b64 s0, s[10:11]
	v_mov_b32_e32 v2, s0
	global_atomic_add v2, v250, v2, s[8:9] offset:1024 sc0
	buffer_inv sc1

; __device__ __forceinline__ unsigned xb_add(unsigned* p, unsigned v) { return __hip_atomic_fetch_add(p, v, __ATOMIC_RELAXED, __HIP_MEMORY_SCOPE_AGENT); }
; __device__ __forceinline__ void xcd_barrier(unsigned* bar, volatile LAS unsigned* st, int wv0) {
;     ...
;             __builtin_amdgcn_fence(__ATOMIC_ACQUIRE, "agent");
;             xb_add(&bar[XB_XGEN(x)], 1u);
;             asm volatile("s_waitcnt vmcnt(0)" ::: "memory");
.LBB0_1659:
	s_or_b64 exec, exec, s[8:9]
	s_mov_b64 s[8:9], exec
	v_mbcnt_lo_u32_b32 v0, s8, 0
	v_mbcnt_hi_u32_b32 v0, s9, v0
	v_cmp_eq_u32_e32 vcc, 0, v0
	s_waitcnt vmcnt(0)
	s_and_saveexec_b64 s[10:11], vcc
	s_cbranch_execnz .LBB0_1660
	s_getpc_b64 s[98:99]
